# norm2 issues gain/shift/scale loads before the row reduction; final norm no longer drains stores before next-row loads
# baseline (speedup 1.0000x reference)
.LBB0_260:
	s_or_b64 exec, exec, s[6:7]
	s_and_b64 s[0:1], exec, vcc
	s_or_b64 s[40:41], s[0:1], s[40:41]
	v_mov_b64_e32 v[54:55], s[66:67]
	v_mov_b32_e32 v43, v129
	s_movk_i32 s0, 0x1fff
	v_add_u32_e32 v39, 0xffffe000, v44
	v_lshrrev_b32_e32 v39, 10, v39
	v_add_u32_e32 v39, 1, v39
	v_cmp_lt_i32_e32 vcc, s0, v44
	v_readlane_b32 s0, v254, 62
	v_mov_b32_e32 v41, v129
	v_cndmask_b32_e32 v39, 0, v39, vcc
	v_add_u32_e32 v39, s0, v39
	s_movk_i32 s0, 0x6000
	v_mad_u64_u32 v[54:55], s[0:1], v39, s0, v[54:55]
	s_mov_b64 s[0:1], 0x3000
	s_nop 0
	v_lshl_add_u64 v[94:95], v[54:55], 0, s[0:1]
	s_mov_b64 s[0:1], 0x4000
	v_lshl_add_u64 v[98:99], v[54:55], 0, s[0:1]
	global_load_dwordx4 v[54:57], v[32:33], off
	v_lshl_add_u64 v[58:59], v[94:95], 0, v[128:129]
	v_lshl_add_u64 v[62:63], v[98:99], 0, v[128:129]
	global_load_dwordx4 v[58:61], v[58:59], off
	s_nop 0
	global_load_dwordx4 v[62:65], v[62:63], off
	s_nop 0
	global_load_dwordx4 v[66:69], v[32:33], off offset:1024
	v_mov_b32_e32 v39, v129
	v_lshl_add_u64 v[70:71], v[94:95], 0, v[38:39]
	v_lshl_add_u64 v[74:75], v[98:99], 0, v[38:39]
	global_load_dwordx4 v[70:73], v[70:71], off
	s_nop 0
	global_load_dwordx4 v[74:77], v[74:75], off
	s_nop 0
	global_load_dwordx4 v[78:81], v[32:33], off offset:2048
	v_lshl_add_u64 v[82:83], v[94:95], 0, v[40:41]
	v_lshl_add_u64 v[86:87], v[98:99], 0, v[40:41]
	global_load_dwordx4 v[82:85], v[82:83], off
	s_nop 0
	global_load_dwordx4 v[86:89], v[86:87], off
	s_nop 0
	global_load_dwordx4 v[90:93], v[32:33], off offset:3072
	v_lshl_add_u64 v[94:95], v[94:95], 0, v[42:43]
	v_lshl_add_u64 v[98:99], v[98:99], 0, v[42:43]
	global_load_dwordx4 v[94:97], v[94:95], off
	global_load_dwordx4 v[98:101], v[98:99], off
	v_lshl_add_u64 v[34:35], v[34:35], 0, s[30:31]
	v_pk_mul_f32 v[114:115], v[12:13], v[12:13]
	v_pk_mul_f32 v[116:117], v[8:9], v[8:9]
	v_pk_mul_f32 v[110:111], v[14:15], v[14:15]
	v_pk_mul_f32 v[112:113], v[10:11], v[10:11]
	v_mov_b32_e32 v118, v114
	v_mov_b32_e32 v119, v116
	v_mov_b32_e32 v116, v115
	v_pk_add_f32 v[114:115], v[118:119], v[116:117]
	v_mov_b32_e32 v116, v110
	v_mov_b32_e32 v117, v112
	v_pk_mul_f32 v[106:107], v[0:1], v[0:1]
	v_pk_mul_f32 v[108:109], v[4:5], v[4:5]
	v_pk_add_f32 v[114:115], v[116:117], v[114:115]
	v_mov_b32_e32 v112, v111
	v_pk_mul_f32 v[102:103], v[2:3], v[2:3]
	v_pk_mul_f32 v[104:105], v[6:7], v[6:7]
	v_pk_add_f32 v[110:111], v[112:113], v[114:115]
	v_mov_b32_e32 v112, v106
	v_mov_b32_e32 v113, v108
	v_mov_b32_e32 v108, v107
	v_pk_add_f32 v[106:107], v[112:113], v[108:109]
	v_mov_b32_e32 v108, v102
	v_mov_b32_e32 v109, v104
	v_pk_add_f32 v[106:107], v[108:109], v[106:107]
	v_mov_b32_e32 v104, v103
	v_pk_add_f32 v[102:103], v[104:105], v[106:107]
	v_add_f32_e32 v120, v110, v111
	v_add_f32_e32 v120, v103, v120
	v_add_f32_e32 v120, v102, v120
	ds_bpermute_b32 v121, v47, v120
	s_mov_b32 s0, 0x800000
	s_waitcnt lgkmcnt(0)
	v_add_f32_e32 v120, v120, v121
	ds_bpermute_b32 v121, v48, v120
	s_waitcnt lgkmcnt(0)
	v_add_f32_e32 v120, v120, v121
	ds_bpermute_b32 v121, v49, v120
	s_waitcnt lgkmcnt(0)
	v_add_f32_e32 v120, v120, v121
	ds_bpermute_b32 v121, v50, v120
	s_waitcnt lgkmcnt(0)
	v_add_f32_e32 v120, v120, v121
	ds_bpermute_b32 v121, v51, v120
	s_waitcnt lgkmcnt(0)
	v_add_f32_e32 v120, v120, v121
	ds_bpermute_b32 v121, v52, v120
	s_waitcnt lgkmcnt(0)
	v_add_f32_e32 v120, v120, v121
	v_fmamk_f32 v120, v120, 0x3a800000, v225
	v_cmp_gt_f32_e32 vcc, s0, v120
	v_mul_f32_e32 v121, 0x4b800000, v120
	s_nop 0
	v_cndmask_b32_e32 v120, v120, v121, vcc
	v_rsq_f32_e32 v120, v120
	s_nop 0
	v_mul_f32_e32 v121, 0x45800000, v120
	v_cndmask_b32_e32 v46, v120, v121, vcc
	v_pk_mul_f32 v[14:15], v[14:15], v[46:47] op_sel_hi:[1,0]
	v_pk_mul_f32 v[12:13], v[12:13], v[46:47] op_sel_hi:[1,0]
	v_pk_mul_f32 v[10:11], v[10:11], v[46:47] op_sel_hi:[1,0]
	v_pk_mul_f32 v[8:9], v[8:9], v[46:47] op_sel_hi:[1,0]
	v_pk_mul_f32 v[6:7], v[6:7], v[46:47] op_sel_hi:[1,0]
	v_pk_mul_f32 v[4:5], v[4:5], v[46:47] op_sel_hi:[1,0]
	v_pk_mul_f32 v[2:3], v[2:3], v[46:47] op_sel_hi:[1,0]
	v_pk_mul_f32 v[0:1], v[0:1], v[46:47] op_sel_hi:[1,0]
	v_mov_b32_e32 v44, v45
	s_waitcnt vmcnt(11)
	v_pk_mul_f32 v[12:13], v[54:55], v[12:13]
	v_pk_mul_f32 v[14:15], v[56:57], v[14:15]
	s_waitcnt vmcnt(9)
	v_pk_add_f32 v[54:55], v[64:65], 1.0 op_sel_hi:[1,0]
	v_pk_add_f32 v[56:57], v[62:63], 1.0 op_sel_hi:[1,0]
	v_pk_fma_f32 v[14:15], v[54:55], v[14:15], v[60:61]
	v_pk_fma_f32 v[12:13], v[56:57], v[12:13], v[58:59]
	s_waitcnt vmcnt(8)
	v_pk_mul_f32 v[8:9], v[66:67], v[8:9]
	v_cvt_pk_bf16_f32 v12, v12, v13
	v_cvt_pk_bf16_f32 v13, v14, v15
	global_store_dwordx2 v[36:37], v[12:13], off offset:-1024
	v_pk_mul_f32 v[10:11], v[68:69], v[10:11]
	s_waitcnt vmcnt(7)
	v_pk_add_f32 v[12:13], v[76:77], 1.0 op_sel_hi:[1,0]
	v_pk_add_f32 v[14:15], v[74:75], 1.0 op_sel_hi:[1,0]
	v_pk_fma_f32 v[10:11], v[12:13], v[10:11], v[72:73]
	v_pk_fma_f32 v[8:9], v[14:15], v[8:9], v[70:71]
	s_waitcnt vmcnt(6)
	v_pk_mul_f32 v[4:5], v[78:79], v[4:5]
	v_cvt_pk_bf16_f32 v8, v8, v9
	v_cvt_pk_bf16_f32 v9, v10, v11
	global_store_dwordx2 v[36:37], v[8:9], off offset:-512
	v_pk_mul_f32 v[6:7], v[80:81], v[6:7]
	s_waitcnt vmcnt(5)
	v_pk_add_f32 v[8:9], v[88:89], 1.0 op_sel_hi:[1,0]
	v_pk_add_f32 v[10:11], v[86:87], 1.0 op_sel_hi:[1,0]
	v_pk_fma_f32 v[6:7], v[8:9], v[6:7], v[84:85]
	v_pk_fma_f32 v[4:5], v[10:11], v[4:5], v[82:83]
	s_waitcnt vmcnt(4)
	v_pk_mul_f32 v[0:1], v[90:91], v[0:1]
	v_cvt_pk_bf16_f32 v4, v4, v5
	v_cvt_pk_bf16_f32 v5, v6, v7
	global_store_dwordx2 v[36:37], v[4:5], off
	v_pk_mul_f32 v[2:3], v[92:93], v[2:3]
	s_waitcnt vmcnt(3)
	v_pk_add_f32 v[4:5], v[100:101], 1.0 op_sel_hi:[1,0]
	v_pk_add_f32 v[6:7], v[98:99], 1.0 op_sel_hi:[1,0]
	v_pk_fma_f32 v[2:3], v[2:3], v[4:5], v[96:97]
	v_pk_fma_f32 v[0:1], v[0:1], v[6:7], v[94:95]
	v_mov_b32_e32 v12, v16
	v_cvt_pk_bf16_f32 v0, v0, v1
	v_cvt_pk_bf16_f32 v1, v2, v3
	global_store_dwordx2 v[36:37], v[0:1], off offset:512
	v_lshl_add_u64 v[36:37], v[36:37], 0, s[38:39]
	v_mov_b32_e32 v13, v17
	v_mov_b32_e32 v14, v18
	v_mov_b32_e32 v15, v19
	v_mov_b32_e32 v8, v20
	v_mov_b32_e32 v9, v21
	v_mov_b32_e32 v10, v22
	v_mov_b32_e32 v11, v23
	v_mov_b32_e32 v4, v24
	v_mov_b32_e32 v5, v25
	v_mov_b32_e32 v6, v26
	v_mov_b32_e32 v7, v27
	v_mov_b32_e32 v0, v28
	v_mov_b32_e32 v1, v29
	v_mov_b32_e32 v2, v30
	v_mov_b32_e32 v3, v31
	s_andn2_b64 exec, exec, s[40:41]
	s_cbranch_execz .LBB0_263

.LBB0_1762:
	v_readlane_b32 s4, v251, 12
	v_ashrrev_i32_e32 v0, 6, v224
	s_movk_i32 s12, 0x3000
	v_add_u32_e32 v32, s4, v0
	s_mov_b64 s[2:3], 0
	v_cmp_gt_i32_e32 vcc, s12, v32
	s_and_saveexec_b64 s[4:5], vcc
	s_cbranch_execz .LBB0_1767
	v_readlane_b32 s8, v250, 1
	s_lshl_b64 s[4:5], s[0:1], 2
	v_readlane_b32 s10, v250, 3
	v_readlane_b32 s11, v250, 4
	s_add_u32 s0, s10, s4
	v_ashrrev_i32_e32 v33, 31, v32
	s_addc_u32 s1, s11, s5
	v_lshlrev_b64 v[16:17], 12, v[32:33]
	v_lshlrev_b32_e32 v2, 4, v224
	v_lshl_add_u64 v[0:1], s[0:1], 0, v[16:17]
	v_and_b32_e32 v18, 0x3f0, v2
	v_mov_b32_e32 v19, 0
	v_lshl_add_u64 v[20:21], v[0:1], 0, v[18:19]
	global_load_dwordx4 v[0:3], v[20:21], off nt
	global_load_dwordx4 v[4:7], v[20:21], off offset:1024 nt
	global_load_dwordx4 v[8:11], v[20:21], off offset:2048 nt
	global_load_dwordx4 v[12:15], v[20:21], off offset:3072 nt
	v_and_b32_e32 v20, 64, v226
	v_add_u32_e32 v20, 64, v20
	v_xor_b32_e32 v21, 32, v226
	v_cmp_lt_i32_e32 vcc, v21, v20
	v_readlane_b32 s0, v251, 7
	v_readlane_b32 s1, v251, 8
	v_cndmask_b32_e32 v21, v226, v21, vcc
	v_lshlrev_b32_e32 v33, 2, v21
	v_xor_b32_e32 v21, 16, v226
	v_cmp_lt_i32_e32 vcc, v21, v20
	s_load_dword s0, s[0:1], 0x0
	v_or_b32_e32 v16, v16, v18
	v_cndmask_b32_e32 v21, v226, v21, vcc
	v_lshlrev_b32_e32 v40, 2, v21
	v_xor_b32_e32 v21, 8, v226
	v_cmp_lt_i32_e32 vcc, v21, v20
	s_waitcnt lgkmcnt(0)
	s_lshl_b32 s6, s0, 3
	v_lshl_add_u64 v[36:37], s[10:11], 0, v[16:17]
	v_cndmask_b32_e32 v21, v226, v21, vcc
	v_lshlrev_b32_e32 v41, 2, v21
	v_xor_b32_e32 v21, 4, v226
	v_cmp_lt_i32_e32 vcc, v21, v20
	v_add_u32_e32 v16, s6, v32
	v_ashrrev_i32_e32 v17, 31, v16
	v_cndmask_b32_e32 v21, v226, v21, vcc
	v_lshlrev_b32_e32 v42, 2, v21
	v_xor_b32_e32 v21, 2, v226
	v_cmp_lt_i32_e32 vcc, v21, v20
	v_lshlrev_b64 v[16:17], 12, v[16:17]
	v_readlane_b32 s9, v250, 2
	v_cndmask_b32_e32 v21, v226, v21, vcc
	v_lshlrev_b32_e32 v43, 2, v21
	v_xor_b32_e32 v21, 1, v226
	v_cmp_lt_i32_e32 vcc, v21, v20
	s_ashr_i32 s7, s6, 31
	v_or_b32_e32 v16, v16, v18
	v_cndmask_b32_e32 v20, v226, v21, vcc
	v_lshlrev_b32_e32 v44, 2, v20
	v_lshl_add_u64 v[34:35], s[8:9], 0, v[18:19]
	s_lshl_b64 s[8:9], s[6:7], 12
	v_lshl_add_u64 v[38:39], s[10:11], 0, v[16:17]
	s_movk_i32 s7, 0x2fff
	v_mov_b32_e32 v45, 0x358637bd
	s_mov_b32 s13, 0x800000
	s_waitcnt vmcnt(0)
	s_branch .LBB0_1765

.LBB0_1765:
	v_add_u32_e32 v32, s6, v32
	v_cmp_gt_i32_e64 s[0:1], s12, v32
	v_cmp_lt_i32_e32 vcc, s7, v32
	v_mov_b32_e32 v28, v0
	v_mov_b32_e32 v29, v1
	v_mov_b32_e32 v30, v2
	v_mov_b32_e32 v31, v3
	v_mov_b32_e32 v16, v4
	v_mov_b32_e32 v17, v5
	v_mov_b32_e32 v18, v6
	v_mov_b32_e32 v19, v7
	v_mov_b32_e32 v20, v8
	v_mov_b32_e32 v21, v9
	v_mov_b32_e32 v22, v10
	v_mov_b32_e32 v23, v11
	v_mov_b32_e32 v24, v12
	v_mov_b32_e32 v25, v13
	v_mov_b32_e32 v26, v14
	v_mov_b32_e32 v27, v15
	s_and_saveexec_b64 s[10:11], s[0:1]
	s_cbranch_execz .LBB0_1764
	v_lshl_add_u64 v[46:47], v[38:39], 0, s[4:5]
	global_load_dwordx4 v[28:31], v[46:47], off nt
	global_load_dwordx4 v[16:19], v[46:47], off offset:1024 nt
	global_load_dwordx4 v[20:23], v[46:47], off offset:2048 nt
	global_load_dwordx4 v[24:27], v[46:47], off offset:3072 nt
	s_branch .LBB0_1764
